# norm2 (NY=1) preamble: scale vectors loaded into spare registers so all 16 per-batch vector loads are in flight together (was 4 serialized round trips); plus hgB DMA and GEMM boundary trims
# speedup vs baseline: 1.0143x; 1.0001x over previous
.LBB0_112:
	s_andn2_b64 vcc, exec, s[2:3]
	s_cbranch_vccnz .LBB0_118
	s_waitcnt vmcnt(0)
	v_mov_b32_e32 v0, v200
	s_load_dword s2, s[38:39], 0x0
	v_ashrrev_i32_e32 v1, 6, v0
	v_add_u32_e32 v64, s61, v1
	s_waitcnt lgkmcnt(0)
	s_bfe_i32 s14, s2, 0x1d0000
	s_abs_i32 s0, s14
	v_cvt_f32_u32_e32 v2, s0
	s_sub_i32 s1, 0, s0
	v_xor_b32_e32 v1, s14, v64
	v_ashrrev_i32_e32 v65, 31, v1
	v_rcp_iflag_f32_e32 v2, v2
	v_sub_u32_e32 v1, 0, v64
	v_max_i32_e32 v1, v64, v1
	v_mul_f32_e32 v2, 0x4f7ffffe, v2
	v_cvt_u32_f32_e32 v2, v2
	v_mul_lo_u32 v3, s1, v2
	v_mul_hi_u32 v3, v2, v3
	v_add_u32_e32 v2, v2, v3
	v_mul_hi_u32 v2, v1, v2
	v_mul_lo_u32 v3, v2, s0
	v_sub_u32_e32 v1, v1, v3
	v_cmp_le_u32_e32 vcc, s0, v1
	v_add_u32_e32 v3, 1, v2
	s_nop 0
	v_cndmask_b32_e32 v2, v2, v3, vcc
	v_subrev_u32_e32 v3, s0, v1
	v_cndmask_b32_e32 v1, v1, v3, vcc
	v_cmp_le_u32_e32 vcc, s0, v1
	v_add_u32_e32 v1, 1, v2
	s_nop 0
	v_cndmask_b32_e32 v1, v2, v1, vcc
	v_xor_b32_e32 v67, v1, v65
	v_sub_u32_e32 v16, v67, v65
	v_cmp_gt_i32_e32 vcc, 8, v16
	s_and_saveexec_b64 s[0:1], vcc
	s_mov_b32 s16, 0x800000
	s_cbranch_execz .LBB0_117
	v_lshlrev_b32_e32 v1, 12, v16
	v_mul_lo_u32 v2, v16, s14
	v_add_u32_e32 v3, v1, v64
	v_sub_u32_e32 v66, v3, v2
	v_add_u32_e32 v77, 0x1000, v1
	v_cmp_lt_i32_e32 vcc, v66, v77
	s_and_b64 exec, exec, vcc
	s_cbranch_execz .LBB0_117
	v_readlane_b32 s6, v255, 29
	v_readlane_b32 s7, v255, 30
	s_lshl_b64 s[6:7], s[6:7], 2
	s_add_u32 s6, s68, s6
	v_and_b32_e32 v68, 63, v0
	s_addc_u32 s7, s69, s7
	v_lshlrev_b32_e32 v128, 4, v68
	global_load_dwordx4 v[0:3], v128, s[6:7]
	global_load_dwordx4 v[4:7], v128, s[6:7] offset:1024
	global_load_dwordx4 v[8:11], v128, s[6:7] offset:2048
	global_load_dwordx4 v[12:15], v128, s[6:7] offset:3072
	v_readlane_b32 s6, v255, 25
	v_readlane_b32 s7, v255, 26
	s_movk_i32 s3, 0x4000
	s_mov_b64 s[12:13], 0x2000
	v_mov_b64_e32 v[18:19], s[6:7]
	v_mad_i64_i32 v[16:17], s[6:7], v16, s84, v[18:19]
	v_lshl_add_u64 v[44:45], v[16:17], 0, v[128:129]
	s_movk_i32 s3, 0x3000
	s_mov_b64 s[6:7], 0x4000
	v_lshl_add_u64 v[28:29], v[44:45], 0, s[6:7]
	s_mov_b64 s[6:7], 0x3000
	v_lshl_add_u64 v[32:33], v[44:45], 0, s[6:7]
	v_lshl_add_u64 v[40:41], v[44:45], 0, s[12:13]
	s_and_b64 s[6:7], s[42:43], exec
	v_readlane_b32 s40, v254, 61
	v_readlane_b32 s41, v254, 62
	s_cselect_b32 s7, s41, s77
	s_cselect_b32 s6, s40, s76
	s_bfe_i32 s13, s2, 0x1001c
	s_bfe_i32 s12, s2, 0x1d0000
	v_readlane_b32 s42, v254, 63
	v_readlane_b32 s43, v255, 0
	v_readlane_b32 s44, v255, 1
	v_readlane_b32 s45, v255, 2
	v_readlane_b32 s46, v255, 3
	v_readlane_b32 s47, v255, 4
	v_readlane_b32 s48, v255, 5
	v_readlane_b32 s49, v255, 6
	v_readlane_b32 s50, v255, 7
	v_readlane_b32 s51, v255, 8
	v_readlane_b32 s52, v255, 9
	v_readlane_b32 s53, v255, 10
	v_readlane_b32 s54, v255, 11
	v_readlane_b32 s55, v255, 12
	s_nop 0
	s_movk_i32 s3, 0x2000
	v_add_co_u32_e32 v44, vcc, s3, v44
	s_lshl_b64 s[2:3], s[12:13], 11
	s_nop 0
	v_addc_co_u32_e32 v45, vcc, 0, v45, vcc
	v_cmp_lt_i32_e32 vcc, v206, v205
	s_nop 1
	v_cndmask_b32_e32 v69, v204, v206, vcc
	v_cmp_lt_i32_e32 vcc, v207, v205
	v_lshlrev_b32_e32 v80, 2, v69
	s_nop 0
	v_cndmask_b32_e32 v69, v204, v207, vcc
	v_cmp_lt_i32_e32 vcc, v252, v205
	v_lshlrev_b32_e32 v81, 2, v69
	s_nop 0
	s_nop 0
	v_cndmask_b32_e32 v69, v204, v252, vcc
	global_load_dwordx4 v[106:109], v[28:29], off
	global_load_dwordx4 v[110:113], v[28:29], off offset:1024
	global_load_dwordx4 v[114:117], v[28:29], off offset:2048
	global_load_dwordx4 v[118:121], v[28:29], off offset:3072
	global_load_dwordx4 v[16:19], v[32:33], off
	global_load_dwordx4 v[20:23], v[32:33], off offset:1024
	global_load_dwordx4 v[24:27], v[32:33], off offset:2048
	global_load_dwordx4 v[28:31], v[32:33], off offset:3072
	global_load_dwordx4 v[32:35], v[40:41], off offset:3072
	global_load_dwordx4 v[36:39], v[40:41], off offset:2048
	global_load_dwordx4 v[40:43], v[40:41], off offset:1024
	global_load_dwordx4 v[44:47], v[44:45], off
	v_lshlrev_b32_e32 v82, 2, v69
	v_xor_b32_e32 v69, 8, v204
	v_cmp_lt_i32_e32 vcc, v69, v205
	s_nop 1
	v_cndmask_b32_e32 v69, v204, v69, vcc
	v_cmp_lt_i32_e32 vcc, v210, v205
	v_lshlrev_b32_e32 v83, 2, v69
	s_nop 0
	v_cndmask_b32_e32 v69, v204, v210, vcc
	v_cmp_lt_i32_e32 vcc, v211, v205
	v_lshlrev_b32_e32 v84, 2, v69
	s_nop 0
	v_cndmask_b32_e32 v69, v204, v211, vcc
	v_lshlrev_b32_e32 v85, 2, v69
	v_sub_u32_e32 v69, v65, v67
	v_mul_lo_u32 v69, v69, s14
	v_lshlrev_b32_e32 v67, 12, v67
	v_add3_u32 v64, v64, v69, v67
	v_lshlrev_b32_e32 v65, 12, v65
	v_ashrrev_i32_e32 v67, 31, v66
	v_sub_u32_e32 v86, v64, v65
	v_lshlrev_b64 v[64:65], 11, v[66:67]
	v_lshlrev_b64 v[66:67], 12, v[66:67]
	v_or_b32_e32 v66, v66, v128
	v_lshl_or_b32 v64, v68, 3, v64
	v_lshl_add_u64 v[66:67], s[6:7], 0, v[66:67]
	s_mov_b64 s[6:7], 0xc00
	v_lshl_add_u64 v[64:65], s[4:5], 0, v[64:65]
	v_lshl_add_u64 v[66:67], v[66:67], 0, s[6:7]
	s_lshl_b64 s[6:7], s[12:13], 12
	s_mov_b64 s[12:13], 0
	s_waitcnt vmcnt(0)
	v_pk_add_f32 v[50:51], v[106:107], 1.0 op_sel_hi:[1,0]
	v_pk_add_f32 v[48:49], v[108:109], 1.0 op_sel_hi:[1,0]
	v_pk_add_f32 v[54:55], v[110:111], 1.0 op_sel_hi:[1,0]
	v_pk_add_f32 v[52:53], v[112:113], 1.0 op_sel_hi:[1,0]
	v_pk_add_f32 v[58:59], v[114:115], 1.0 op_sel_hi:[1,0]
	v_pk_add_f32 v[56:57], v[116:117], 1.0 op_sel_hi:[1,0]
	v_pk_add_f32 v[62:63], v[118:119], 1.0 op_sel_hi:[1,0]
	v_pk_add_f32 v[60:61], v[120:121], 1.0 op_sel_hi:[1,0]
